# speedup vs baseline: 1.0111x; 1.0053x over previous
; __device__ __forceinline__ void attn_diff(const bf16* __restrict__ Qg, const bf16* __restrict__ Kg, const bf16* __restrict__ Vg, int vts, ...
;     ...
;     if (arrived + 1u < (unsigned)nchunk) {
;       float* slab = sslab + (size_t)arrived * (66 * NTHR);
;       if (has) {
; #pragma unroll
;         for (int dt = 0; dt < 4; ++dt)
; #pragma unroll
;           for (int r = 0; r < 16; ++r) slab[(dt * 16 + r) * NTHR + tidx] = O[dt][r];
;         slab[64 * NTHR + tidx] = l; slab[65 * NTHR + tidx] = mref;
;       }
;       asm volatile("s_waitcnt vmcnt(0)" ::: "memory");
;       __syncthreads();
;       if (tidx == 0) {
;         __builtin_amdgcn_fence(__ATOMIC_RELEASE, "agent");
;         asm volatile("s_waitcnt vmcnt(0)" ::: "memory");
;         __hip_atomic_store(sctl + 1 + arrived, 1u, __ATOMIC_RELAXED, __HIP_MEMORY_SCOPE_AGENT);
.LBB0_268:
	s_andn2_saveexec_b64 s[0:1], s[0:1]
	s_cbranch_execz .LBB0_274
	s_and_saveexec_b64 s[6:7], s[44:45]
	s_cbranch_execz .LBB0_271
	v_readlane_b32 s8, v255, 9
	v_readlane_b32 s9, v255, 10
	v_ashrrev_i32_e32 v151, 31, v150
	v_ashrrev_i32_e32 v155, 31, v154
	v_lshl_add_u64 v[4:5], s[8:9], 0, v[8:9]
	s_mov_b64 s[8:9], 0xee00000
	v_lshl_add_u64 v[4:5], v[4:5], 0, s[8:9]
	s_mov_b32 s8, 0x21000
	v_mad_u64_u32 v[8:9], s[8:9], v0, s8, v[4:5]
	v_lshl_add_u64 v[4:5], v[150:151], 2, v[8:9]
	v_lshl_add_u64 v[10:11], v[154:155], 2, v[8:9]
	v_ashrrev_i32_e32 v157, 31, v156
	flat_store_dword v[4:5], v64 sc1
	flat_store_dword v[4:5], v65 offset:2048 sc1
	flat_store_dword v[10:11], v66 sc1
	v_lshl_add_u64 v[10:11], v[156:157], 2, v[8:9]
	flat_store_dword v[10:11], v67 sc1
	v_add_u32_e32 v10, 0x800, v150
	v_ashrrev_i32_e32 v11, 31, v10
	v_lshl_add_u64 v[10:11], v[10:11], 2, v[8:9]
	flat_store_dword v[10:11], v68 sc1
	v_add_u32_e32 v10, 0xa00, v150
	v_ashrrev_i32_e32 v11, 31, v10
	v_lshl_add_u64 v[10:11], v[10:11], 2, v[8:9]
	flat_store_dword v[10:11], v69 sc1
	v_add_u32_e32 v10, 0xc00, v150
	v_ashrrev_i32_e32 v11, 31, v10
	v_lshl_add_u64 v[10:11], v[10:11], 2, v[8:9]
	flat_store_dword v[10:11], v70 sc1
	v_add_u32_e32 v10, 0xe00, v150
	v_ashrrev_i32_e32 v11, 31, v10
	v_lshl_add_u64 v[10:11], v[10:11], 2, v[8:9]
	flat_store_dword v[10:11], v71 sc1
	v_add_u32_e32 v10, 0x1000, v150
	v_ashrrev_i32_e32 v11, 31, v10
	v_lshl_add_u64 v[10:11], v[10:11], 2, v[8:9]
	flat_store_dword v[10:11], v72 sc1
	v_add_u32_e32 v10, 0x1200, v150
	v_ashrrev_i32_e32 v11, 31, v10
	v_lshl_add_u64 v[10:11], v[10:11], 2, v[8:9]
	flat_store_dword v[10:11], v73 sc1
	v_add_u32_e32 v10, 0x1400, v150
	v_ashrrev_i32_e32 v11, 31, v10
	v_lshl_add_u64 v[10:11], v[10:11], 2, v[8:9]
	flat_store_dword v[10:11], v74 sc1
	v_add_u32_e32 v10, 0x1600, v150
	v_ashrrev_i32_e32 v11, 31, v10
	v_lshl_add_u64 v[10:11], v[10:11], 2, v[8:9]
	flat_store_dword v[10:11], v75 sc1
	v_add_u32_e32 v10, 0x1800, v150
	v_ashrrev_i32_e32 v11, 31, v10
	v_lshl_add_u64 v[10:11], v[10:11], 2, v[8:9]
	flat_store_dword v[10:11], v76 sc1
	v_add_u32_e32 v10, 0x1a00, v150
	v_ashrrev_i32_e32 v11, 31, v10
	v_lshl_add_u64 v[10:11], v[10:11], 2, v[8:9]
	flat_store_dword v[10:11], v77 sc1
	v_add_u32_e32 v10, 0x1c00, v150
	v_ashrrev_i32_e32 v11, 31, v10
	v_lshl_add_u64 v[10:11], v[10:11], 2, v[8:9]
	flat_store_dword v[10:11], v78 sc1
	v_add_u32_e32 v10, 0x1e00, v150
	v_ashrrev_i32_e32 v11, 31, v10
	v_lshl_add_u64 v[10:11], v[10:11], 2, v[8:9]
	flat_store_dword v[10:11], v79 sc1
	v_add_u32_e32 v10, 0x2000, v150
	v_ashrrev_i32_e32 v11, 31, v10
	v_lshl_add_u64 v[10:11], v[10:11], 2, v[8:9]
	flat_store_dword v[10:11], v48 sc1
	v_add_u32_e32 v10, 0x2200, v150
	v_ashrrev_i32_e32 v11, 31, v10
	v_lshl_add_u64 v[10:11], v[10:11], 2, v[8:9]
	flat_store_dword v[10:11], v49 sc1
	v_add_u32_e32 v10, 0x2400, v150
	v_ashrrev_i32_e32 v11, 31, v10
	v_lshl_add_u64 v[10:11], v[10:11], 2, v[8:9]
	flat_store_dword v[10:11], v50 sc1
	v_add_u32_e32 v10, 0x2600, v150
	v_ashrrev_i32_e32 v11, 31, v10
	v_lshl_add_u64 v[10:11], v[10:11], 2, v[8:9]
	flat_store_dword v[10:11], v51 sc1
	v_add_u32_e32 v10, 0x2800, v150
	v_ashrrev_i32_e32 v11, 31, v10
	v_lshl_add_u64 v[10:11], v[10:11], 2, v[8:9]
	flat_store_dword v[10:11], v52 sc1
	v_add_u32_e32 v10, 0x2a00, v150
	v_ashrrev_i32_e32 v11, 31, v10
	v_lshl_add_u64 v[10:11], v[10:11], 2, v[8:9]
	flat_store_dword v[10:11], v53 sc1
	v_add_u32_e32 v10, 0x2c00, v150
	v_ashrrev_i32_e32 v11, 31, v10
	v_lshl_add_u64 v[10:11], v[10:11], 2, v[8:9]
	flat_store_dword v[10:11], v54 sc1
	v_add_u32_e32 v10, 0x2e00, v150
	v_ashrrev_i32_e32 v11, 31, v10
	v_lshl_add_u64 v[10:11], v[10:11], 2, v[8:9]
	flat_store_dword v[10:11], v55 sc1
	v_add_u32_e32 v10, 0x3000, v150
	v_ashrrev_i32_e32 v11, 31, v10
	v_lshl_add_u64 v[10:11], v[10:11], 2, v[8:9]
	flat_store_dword v[10:11], v56 sc1
	v_add_u32_e32 v10, 0x3200, v150
	v_ashrrev_i32_e32 v11, 31, v10
	v_lshl_add_u64 v[10:11], v[10:11], 2, v[8:9]
	flat_store_dword v[10:11], v57 sc1
	v_add_u32_e32 v10, 0x3400, v150
	v_ashrrev_i32_e32 v11, 31, v10
	v_lshl_add_u64 v[10:11], v[10:11], 2, v[8:9]
	flat_store_dword v[10:11], v58 sc1
	v_add_u32_e32 v10, 0x3600, v150
	v_ashrrev_i32_e32 v11, 31, v10
	v_lshl_add_u64 v[10:11], v[10:11], 2, v[8:9]
	flat_store_dword v[10:11], v59 sc1
	v_add_u32_e32 v10, 0x3800, v150
	v_ashrrev_i32_e32 v11, 31, v10
	v_lshl_add_u64 v[10:11], v[10:11], 2, v[8:9]
	flat_store_dword v[10:11], v60 sc1
	v_add_u32_e32 v10, 0x3a00, v150
	v_ashrrev_i32_e32 v11, 31, v10
	v_lshl_add_u64 v[10:11], v[10:11], 2, v[8:9]
	flat_store_dword v[10:11], v61 sc1
	v_add_u32_e32 v10, 0x3c00, v150
	v_ashrrev_i32_e32 v11, 31, v10
	v_lshl_add_u64 v[10:11], v[10:11], 2, v[8:9]
	flat_store_dword v[10:11], v62 sc1
	v_add_u32_e32 v10, 0x3e00, v150
	v_ashrrev_i32_e32 v11, 31, v10
	v_lshl_add_u64 v[10:11], v[10:11], 2, v[8:9]
	flat_store_dword v[10:11], v63 sc1
	v_add_u32_e32 v10, 0x4000, v150
	v_ashrrev_i32_e32 v11, 31, v10
	v_lshl_add_u64 v[10:11], v[10:11], 2, v[8:9]
; __device__ __forceinline__ void attn_diff(const bf16* __restrict__ Qg, const bf16* __restrict__ Kg, const bf16* __restrict__ Vg, int vts, ...
;     ...
;       float* slab = sslab + (size_t)arrived * (66 * NTHR);
;       if (has) {
; #pragma unroll
;         for (int dt = 0; dt < 4; ++dt)
; #pragma unroll
;           for (int r = 0; r < 16; ++r) slab[(dt * 16 + r) * NTHR + tidx] = O[dt][r];
;         slab[64 * NTHR + tidx] = l; slab[65 * NTHR + tidx] = mref;
;       }
;       asm volatile("s_waitcnt vmcnt(0)" ::: "memory");
;       __syncthreads();
;       if (tidx == 0) {
;         __builtin_amdgcn_fence(__ATOMIC_RELEASE, "agent");
;         asm volatile("s_waitcnt vmcnt(0)" ::: "memory");
;         __hip_atomic_store(sctl + 1 + arrived, 1u, __ATOMIC_RELAXED, __HIP_MEMORY_SCOPE_AGENT);
	flat_store_dword v[10:11], v32 sc1
	v_add_u32_e32 v10, 0x4200, v150
	v_ashrrev_i32_e32 v11, 31, v10
	v_lshl_add_u64 v[10:11], v[10:11], 2, v[8:9]
	flat_store_dword v[10:11], v33 sc1
	v_add_u32_e32 v10, 0x4400, v150
	v_ashrrev_i32_e32 v11, 31, v10
	v_lshl_add_u64 v[10:11], v[10:11], 2, v[8:9]
	flat_store_dword v[10:11], v34 sc1
	v_add_u32_e32 v10, 0x4600, v150
	v_ashrrev_i32_e32 v11, 31, v10
	v_lshl_add_u64 v[10:11], v[10:11], 2, v[8:9]
	flat_store_dword v[10:11], v35 sc1
	v_add_u32_e32 v10, 0x4800, v150
	v_ashrrev_i32_e32 v11, 31, v10
	v_lshl_add_u64 v[10:11], v[10:11], 2, v[8:9]
	flat_store_dword v[10:11], v36 sc1
	v_add_u32_e32 v10, 0x4a00, v150
	v_ashrrev_i32_e32 v11, 31, v10
	v_lshl_add_u64 v[10:11], v[10:11], 2, v[8:9]
	flat_store_dword v[10:11], v37 sc1
	v_add_u32_e32 v10, 0x4c00, v150
	v_ashrrev_i32_e32 v11, 31, v10
	v_lshl_add_u64 v[10:11], v[10:11], 2, v[8:9]
	flat_store_dword v[10:11], v38 sc1
	v_add_u32_e32 v10, 0x4e00, v150
	v_ashrrev_i32_e32 v11, 31, v10
	v_lshl_add_u64 v[10:11], v[10:11], 2, v[8:9]
	flat_store_dword v[10:11], v39 sc1
	v_add_u32_e32 v10, 0x5000, v150
	v_ashrrev_i32_e32 v11, 31, v10
	v_lshl_add_u64 v[10:11], v[10:11], 2, v[8:9]
	flat_store_dword v[10:11], v40 sc1
	v_add_u32_e32 v10, 0x5200, v150
	v_ashrrev_i32_e32 v11, 31, v10
	v_lshl_add_u64 v[10:11], v[10:11], 2, v[8:9]
	flat_store_dword v[10:11], v41 sc1
	v_add_u32_e32 v10, 0x5400, v150
	v_ashrrev_i32_e32 v11, 31, v10
	v_lshl_add_u64 v[10:11], v[10:11], 2, v[8:9]
	flat_store_dword v[10:11], v42 sc1
	v_add_u32_e32 v10, 0x5600, v150
	v_ashrrev_i32_e32 v11, 31, v10
	v_lshl_add_u64 v[10:11], v[10:11], 2, v[8:9]
	flat_store_dword v[10:11], v43 sc1
	v_add_u32_e32 v10, 0x5800, v150
	v_ashrrev_i32_e32 v11, 31, v10
	v_lshl_add_u64 v[10:11], v[10:11], 2, v[8:9]
	flat_store_dword v[10:11], v44 sc1
	v_add_u32_e32 v10, 0x5a00, v150
	v_ashrrev_i32_e32 v11, 31, v10
	v_lshl_add_u64 v[10:11], v[10:11], 2, v[8:9]
	flat_store_dword v[10:11], v45 sc1
	v_add_u32_e32 v10, 0x5c00, v150
	v_ashrrev_i32_e32 v11, 31, v10
	v_lshl_add_u64 v[10:11], v[10:11], 2, v[8:9]
	flat_store_dword v[10:11], v46 sc1
	v_add_u32_e32 v10, 0x5e00, v150
	v_ashrrev_i32_e32 v11, 31, v10
	v_lshl_add_u64 v[10:11], v[10:11], 2, v[8:9]
	flat_store_dword v[10:11], v47 sc1
	v_add_u32_e32 v10, 0x6000, v150
	v_ashrrev_i32_e32 v11, 31, v10
	v_lshl_add_u64 v[10:11], v[10:11], 2, v[8:9]
	flat_store_dword v[10:11], v16 sc1
	v_add_u32_e32 v10, 0x6200, v150
	v_ashrrev_i32_e32 v11, 31, v10
	v_lshl_add_u64 v[10:11], v[10:11], 2, v[8:9]
	flat_store_dword v[10:11], v17 sc1
	v_add_u32_e32 v10, 0x6400, v150
	v_ashrrev_i32_e32 v11, 31, v10
	v_lshl_add_u64 v[10:11], v[10:11], 2, v[8:9]
	flat_store_dword v[10:11], v18 sc1
	v_add_u32_e32 v10, 0x6600, v150
	v_ashrrev_i32_e32 v11, 31, v10
	v_lshl_add_u64 v[10:11], v[10:11], 2, v[8:9]
	flat_store_dword v[10:11], v19 sc1
	v_add_u32_e32 v10, 0x6800, v150
	v_ashrrev_i32_e32 v11, 31, v10
	v_lshl_add_u64 v[10:11], v[10:11], 2, v[8:9]
	flat_store_dword v[10:11], v20 sc1
	v_add_u32_e32 v10, 0x6a00, v150
	v_ashrrev_i32_e32 v11, 31, v10
	v_lshl_add_u64 v[10:11], v[10:11], 2, v[8:9]
	flat_store_dword v[10:11], v21 sc1
	v_add_u32_e32 v10, 0x6c00, v150
	v_ashrrev_i32_e32 v11, 31, v10
	v_lshl_add_u64 v[10:11], v[10:11], 2, v[8:9]
	flat_store_dword v[10:11], v22 sc1
	v_add_u32_e32 v10, 0x6e00, v150
	v_ashrrev_i32_e32 v11, 31, v10
	v_lshl_add_u64 v[10:11], v[10:11], 2, v[8:9]
	flat_store_dword v[10:11], v23 sc1
	v_add_u32_e32 v10, 0x7000, v150
	v_ashrrev_i32_e32 v11, 31, v10
	v_lshl_add_u64 v[10:11], v[10:11], 2, v[8:9]
	flat_store_dword v[10:11], v24 sc1
	v_add_u32_e32 v10, 0x7200, v150
	v_ashrrev_i32_e32 v11, 31, v10
	v_lshl_add_u64 v[10:11], v[10:11], 2, v[8:9]
	flat_store_dword v[10:11], v25 sc1
	v_add_u32_e32 v10, 0x7400, v150
	v_ashrrev_i32_e32 v11, 31, v10
	v_lshl_add_u64 v[10:11], v[10:11], 2, v[8:9]
	flat_store_dword v[10:11], v26 sc1
	v_add_u32_e32 v10, 0x7600, v150
	v_ashrrev_i32_e32 v11, 31, v10
	v_lshl_add_u64 v[10:11], v[10:11], 2, v[8:9]
	flat_store_dword v[10:11], v27 sc1
	v_add_u32_e32 v10, 0x7800, v150
	v_ashrrev_i32_e32 v11, 31, v10
	v_lshl_add_u64 v[10:11], v[10:11], 2, v[8:9]
	flat_store_dword v[10:11], v28 sc1
	v_add_u32_e32 v10, 0x7a00, v150
	v_ashrrev_i32_e32 v11, 31, v10
	v_lshl_add_u64 v[10:11], v[10:11], 2, v[8:9]
	flat_store_dword v[10:11], v29 sc1
	v_add_u32_e32 v10, 0x7c00, v150
	v_ashrrev_i32_e32 v11, 31, v10
	v_lshl_add_u64 v[10:11], v[10:11], 2, v[8:9]
	flat_store_dword v[10:11], v30 sc1
	v_add_u32_e32 v10, 0x7e00, v150
	v_ashrrev_i32_e32 v11, 31, v10
	v_add_co_u32_e32 v4, vcc, 0x20000, v4
	v_lshl_add_u64 v[8:9], v[10:11], 2, v[8:9]
	s_nop 0
	v_addc_co_u32_e32 v5, vcc, 0, v5, vcc
	flat_store_dword v[8:9], v31 sc1
	flat_store_dword v[4:5], v224 sc1
	flat_store_dword v[4:5], v2 offset:2048 sc1
.LBB0_271:
	s_or_b64 exec, exec, s[6:7]
	s_waitcnt vmcnt(0)
	s_waitcnt lgkmcnt(0)
	s_barrier
	s_and_saveexec_b64 s[6:7], s[10:11]
	s_cbranch_execz .LBB0_273
	s_waitcnt vmcnt(0)
	v_lshl_add_u64 v[2:3], v[0:1], 2, v[6:7]
	flat_store_dword v[2:3], v191 offset:4 sc1
